# hot loop heads pinned to 64-byte boundaries (in_proj K-loop head at 4 mod 8, attention tile loop at 0 mod 8), on top of fused S1 scan + rcp epilogues + attention nop trimming + mod GEMV rolling loads
# speedup vs baseline: 1.0460x; 1.0007x over previous
; template <bool SP2 = true, class Epi, class Sched>
; __device__ __forceinline__ void gemm_phase(LAS unsigned char* lds, const int K, const int lda, const int ldb, const Sched& S, const Epi& E) {
;     ...
;     f32x4 acc[2][2][4][2];
; #pragma unroll
;     for (int a = 0; a < 2; ++a)
; #pragma unroll
;         for (int b = 0; b < 2; ++b)
; #pragma unroll
;             for (int m = 0; m < 4; ++m)
; #pragma unroll
;                 for (int n = 0; n < 2; ++n) acc[a][b][m][n] = (f32x4){0.f, 0.f, 0.f, 0.f};
.LBB0_253:
	s_add_u32 s8, s8, 0x80080
	s_addc_u32 s9, s9, 0
	s_add_u32 s25, s10, 0x100
	v_mov_b32_e32 v0, 0
	s_addc_u32 s27, s11, 0
	s_mov_b32 s38, -2
	v_mov_b32_e32 v1, v0
	v_mov_b32_e32 v2, v0
	v_mov_b32_e32 v3, v0
	v_mov_b32_e32 v4, v0
	v_mov_b32_e32 v5, v0
	v_mov_b32_e32 v6, v0
	v_mov_b32_e32 v7, v0
	v_mov_b32_e32 v16, v0
	v_mov_b32_e32 v17, v0
	v_mov_b32_e32 v18, v0
	v_mov_b32_e32 v19, v0
	v_mov_b32_e32 v20, v0
	v_mov_b32_e32 v21, v0
	v_mov_b32_e32 v22, v0
	v_mov_b32_e32 v23, v0
	v_mov_b32_e32 v32, v0
	v_mov_b32_e32 v33, v0
	v_mov_b32_e32 v34, v0
	v_mov_b32_e32 v35, v0
	v_mov_b32_e32 v36, v0
	v_mov_b32_e32 v37, v0
	v_mov_b32_e32 v38, v0
	v_mov_b32_e32 v39, v0
	v_mov_b32_e32 v48, v0
	v_mov_b32_e32 v49, v0
	v_mov_b32_e32 v50, v0
	v_mov_b32_e32 v51, v0
	v_mov_b32_e32 v52, v0
	v_mov_b32_e32 v53, v0
	v_mov_b32_e32 v54, v0
	v_mov_b32_e32 v55, v0
	v_mov_b32_e32 v8, v0
	v_mov_b32_e32 v9, v0
	v_mov_b32_e32 v10, v0
	v_mov_b32_e32 v11, v0
	v_mov_b32_e32 v12, v0
	v_mov_b32_e32 v13, v0
	v_mov_b32_e32 v14, v0
	v_mov_b32_e32 v15, v0
	v_mov_b32_e32 v24, v0
	v_mov_b32_e32 v25, v0
	v_mov_b32_e32 v26, v0
	v_mov_b32_e32 v27, v0
	v_mov_b32_e32 v28, v0
	v_mov_b32_e32 v29, v0
	v_mov_b32_e32 v30, v0
	v_mov_b32_e32 v31, v0
	v_mov_b32_e32 v40, v0
	v_mov_b32_e32 v41, v0
	v_mov_b32_e32 v42, v0
	v_mov_b32_e32 v43, v0
	v_mov_b32_e32 v44, v0
	v_mov_b32_e32 v45, v0
	v_mov_b32_e32 v46, v0
	v_mov_b32_e32 v47, v0
	v_mov_b32_e32 v56, v0
	v_mov_b32_e32 v57, v0
	v_mov_b32_e32 v58, v0
	v_mov_b32_e32 v59, v0
	v_mov_b32_e32 v60, v0
	v_mov_b32_e32 v61, v0
	v_mov_b32_e32 v62, v0
	v_mov_b32_e32 v63, v0
	v_mov_b32_e32 v64, v0
	v_mov_b32_e32 v65, v0
	v_mov_b32_e32 v66, v0
	v_mov_b32_e32 v67, v0
	v_mov_b32_e32 v68, v0
	v_mov_b32_e32 v69, v0
	v_mov_b32_e32 v70, v0
	v_mov_b32_e32 v71, v0
	v_mov_b32_e32 v80, v0
	v_mov_b32_e32 v81, v0
	v_mov_b32_e32 v82, v0
	v_mov_b32_e32 v83, v0
	v_mov_b32_e32 v84, v0
	v_mov_b32_e32 v85, v0
	v_mov_b32_e32 v86, v0
	v_mov_b32_e32 v87, v0
	v_mov_b32_e32 v96, v0
	v_mov_b32_e32 v97, v0
	v_mov_b32_e32 v98, v0
	v_mov_b32_e32 v99, v0
	v_mov_b32_e32 v100, v0
	v_mov_b32_e32 v101, v0
	v_mov_b32_e32 v102, v0
	v_mov_b32_e32 v103, v0
	v_mov_b32_e32 v112, v0
	v_mov_b32_e32 v113, v0
	v_mov_b32_e32 v114, v0
	v_mov_b32_e32 v115, v0
	v_mov_b32_e32 v116, v0
	v_mov_b32_e32 v117, v0
	v_mov_b32_e32 v118, v0
	v_mov_b32_e32 v119, v0
	v_mov_b32_e32 v72, v0
	v_mov_b32_e32 v73, v0
	v_mov_b32_e32 v74, v0
	v_mov_b32_e32 v75, v0
	v_mov_b32_e32 v76, v0
	v_mov_b32_e32 v77, v0
	v_mov_b32_e32 v78, v0
	v_mov_b32_e32 v79, v0
	v_mov_b32_e32 v88, v0
	v_mov_b32_e32 v89, v0
	v_mov_b32_e32 v90, v0
	v_mov_b32_e32 v91, v0
	v_mov_b32_e32 v92, v0
	v_mov_b32_e32 v93, v0
	v_mov_b32_e32 v94, v0
	v_mov_b32_e32 v95, v0
	v_mov_b32_e32 v104, v0
	v_mov_b32_e32 v105, v0
	v_mov_b32_e32 v106, v0
	v_mov_b32_e32 v107, v0
	v_mov_b32_e32 v108, v0
	v_mov_b32_e32 v109, v0
	v_mov_b32_e32 v110, v0
	v_mov_b32_e32 v111, v0
	v_mov_b32_e32 v120, v0
	v_mov_b32_e32 v121, v0
	v_mov_b32_e32 v122, v0
	v_mov_b32_e32 v123, v0
	v_mov_b32_e32 v124, v0
	v_mov_b32_e32 v125, v0
	v_mov_b32_e32 v126, v0
	v_mov_b32_e32 v127, v0
	.p2align 6
	s_nop 0

; template <bool SP2 = true, class Epi, class Sched>
; __device__ __forceinline__ void gemm_phase(LAS unsigned char* lds, const int K, const int lda, const int ldb, const Sched& S, const Epi& E) {
;     ...
;     f32x4 acc[2][2][4][2];
; #pragma unroll
;     for (int a = 0; a < 2; ++a)
; #pragma unroll
;         for (int b = 0; b < 2; ++b)
; #pragma unroll
;             for (int m = 0; m < 4; ++m)
; #pragma unroll
;                 for (int n = 0; n < 2; ++n) acc[a][b][m][n] = (f32x4){0.f, 0.f, 0.f, 0.f};
.LBB0_390:
	s_add_u32 s17, s26, 0x100
	v_mov_b32_e32 v0, 0
	s_addc_u32 s90, s27, 0
	s_mov_b32 s91, -2
	v_mov_b32_e32 v1, v0
	v_mov_b32_e32 v2, v0
	v_mov_b32_e32 v3, v0
	v_mov_b32_e32 v4, v0
	v_mov_b32_e32 v5, v0
	v_mov_b32_e32 v6, v0
	v_mov_b32_e32 v7, v0
	v_mov_b32_e32 v8, v0
	v_mov_b32_e32 v9, v0
	v_mov_b32_e32 v10, v0
	v_mov_b32_e32 v11, v0
	v_mov_b32_e32 v12, v0
	v_mov_b32_e32 v13, v0
	v_mov_b32_e32 v14, v0
	v_mov_b32_e32 v15, v0
	v_mov_b32_e32 v24, v0
	v_mov_b32_e32 v25, v0
	v_mov_b32_e32 v26, v0
	v_mov_b32_e32 v27, v0
	v_mov_b32_e32 v28, v0
	v_mov_b32_e32 v29, v0
	v_mov_b32_e32 v30, v0
	v_mov_b32_e32 v31, v0
	v_mov_b32_e32 v40, v0
	v_mov_b32_e32 v41, v0
	v_mov_b32_e32 v42, v0
	v_mov_b32_e32 v43, v0
	v_mov_b32_e32 v44, v0
	v_mov_b32_e32 v45, v0
	v_mov_b32_e32 v46, v0
	v_mov_b32_e32 v47, v0
	v_mov_b32_e32 v16, v0
	v_mov_b32_e32 v17, v0
	v_mov_b32_e32 v18, v0
	v_mov_b32_e32 v19, v0
	v_mov_b32_e32 v20, v0
	v_mov_b32_e32 v21, v0
	v_mov_b32_e32 v22, v0
	v_mov_b32_e32 v23, v0
	v_mov_b32_e32 v32, v0
	v_mov_b32_e32 v33, v0
	v_mov_b32_e32 v34, v0
	v_mov_b32_e32 v35, v0
	v_mov_b32_e32 v36, v0
	v_mov_b32_e32 v37, v0
	v_mov_b32_e32 v38, v0
	v_mov_b32_e32 v39, v0
	v_mov_b32_e32 v48, v0
	v_mov_b32_e32 v49, v0
	v_mov_b32_e32 v50, v0
	v_mov_b32_e32 v51, v0
	v_mov_b32_e32 v52, v0
	v_mov_b32_e32 v53, v0
	v_mov_b32_e32 v54, v0
	v_mov_b32_e32 v55, v0
	v_mov_b32_e32 v56, v0
	v_mov_b32_e32 v57, v0
	v_mov_b32_e32 v58, v0
	v_mov_b32_e32 v59, v0
	v_mov_b32_e32 v60, v0
	v_mov_b32_e32 v61, v0
	v_mov_b32_e32 v62, v0
	v_mov_b32_e32 v63, v0
	v_mov_b32_e32 v64, v0
	v_mov_b32_e32 v65, v0
	v_mov_b32_e32 v66, v0
	v_mov_b32_e32 v67, v0
	v_mov_b32_e32 v68, v0
	v_mov_b32_e32 v69, v0
	v_mov_b32_e32 v70, v0
	v_mov_b32_e32 v71, v0
	v_mov_b32_e32 v72, v0
	v_mov_b32_e32 v73, v0
	v_mov_b32_e32 v74, v0
	v_mov_b32_e32 v75, v0
	v_mov_b32_e32 v76, v0
	v_mov_b32_e32 v77, v0
	v_mov_b32_e32 v78, v0
	v_mov_b32_e32 v79, v0
	v_mov_b32_e32 v88, v0
	v_mov_b32_e32 v89, v0
	v_mov_b32_e32 v90, v0
	v_mov_b32_e32 v91, v0
	v_mov_b32_e32 v92, v0
	v_mov_b32_e32 v93, v0
	v_mov_b32_e32 v94, v0
	v_mov_b32_e32 v95, v0
	v_mov_b32_e32 v104, v0
	v_mov_b32_e32 v105, v0
	v_mov_b32_e32 v106, v0
	v_mov_b32_e32 v107, v0
	v_mov_b32_e32 v108, v0
	v_mov_b32_e32 v109, v0
	v_mov_b32_e32 v110, v0
	v_mov_b32_e32 v111, v0
	v_mov_b32_e32 v80, v0
	v_mov_b32_e32 v81, v0
	v_mov_b32_e32 v82, v0
	v_mov_b32_e32 v83, v0
	v_mov_b32_e32 v84, v0
	v_mov_b32_e32 v85, v0
	v_mov_b32_e32 v86, v0
	v_mov_b32_e32 v87, v0
	v_mov_b32_e32 v96, v0
	v_mov_b32_e32 v97, v0
	v_mov_b32_e32 v98, v0
	v_mov_b32_e32 v99, v0
	v_mov_b32_e32 v100, v0
	v_mov_b32_e32 v101, v0
	v_mov_b32_e32 v102, v0
	v_mov_b32_e32 v103, v0
	v_mov_b32_e32 v112, v0
	v_mov_b32_e32 v113, v0
	v_mov_b32_e32 v114, v0
	v_mov_b32_e32 v115, v0
	v_mov_b32_e32 v116, v0
	v_mov_b32_e32 v117, v0
	v_mov_b32_e32 v118, v0
	v_mov_b32_e32 v119, v0
	v_mov_b32_e32 v120, v0
	v_mov_b32_e32 v121, v0
	v_mov_b32_e32 v122, v0
	v_mov_b32_e32 v123, v0
	v_mov_b32_e32 v124, v0
	v_mov_b32_e32 v125, v0
	v_mov_b32_e32 v126, v0
	v_mov_b32_e32 v127, v0
	.p2align 6

; __device__ __forceinline__ int opaque_tid() { int t = threadIdx.x; asm volatile("" : "+v"(t)); return t; }
; #define ATT_MFMA(a, b, c) __builtin_amdgcn_mfma_f32_32x32x16_bf16(a, b, c, 0, 0, 0)
; __device__ __forceinline__ void attn_unit(LAS unsigned char* lds, const bf16_t* PROJ, bf16_t* OCAT, const float* subg, float lam, float oml, int b, int h, int qb) {
;     const int tid = opaque_tid(), lane = tid & 63, r32 = lane & 31, hi = lane >> 5, wid = __builtin_amdgcn_readfirstlane(tid >> 6), comp = wid >> 2, wq = wid & 3;
;     const size_t rowbase = (size_t)b * SEQ; const int q0 = qb * 128;
;     bf16x8 qr[4];
;     { const bf16_t* qp = PROJ + (rowbase + q0 + wq * 32 + r32) * PP + h * 128 + comp * 64 + hi * 8;
; #pragma unroll
;       for (int d0 = 0; d0 < 4; ++d0) qr[d0] = *(const bf16x8*)(qp + d0 * 16); }
;     constexpr int KSL = 18432, VB = 2 * KSL, VSL = 20480;
;     const int krow = tid >> 3, kch = tid & 7, vrow0 = tid >> 4, vch = tid & 15;
;     const bf16_t* kg = PROJ + (rowbase + krow) * PP + C_K + h * 128 + kch * 8;
;     const bf16_t* vg = PROJ + (rowbase + vrow0) * PP + C_V + h * 128 + vch * 8;
;     const int kst = krow * 144 + kch * 16, vst = VB + vrow0 * 320 + vch * 16;
;     const int rot = qb * 2;
;     u32x4 ga0, ga1, ga2, ga3;
;     ...
;     const int kread = comp * 9216 + r32 * 144 + hi * 16;
;     const int vread = VB + (4 * hi + ((lane & 15) >> 2)) * 320 + ((lane >> 4) & 1) * 32 + (lane & 3) * 8;
;     f32x16 o[4];
; #pragma unroll
;     for (int i = 0; i < 4; ++i)
; #pragma unroll
;         for (int r = 0; r < 16; ++r) o[i][r] = 0.f;
;     float mrun, lrun = 0.f;
;     f32x16 pA0, pA1, pB0, pB1, negm;
;     const f32x16 zero16 = {0.f, 0.f, 0.f, 0.f, 0.f, 0.f, 0.f, 0.f, 0.f, 0.f, 0.f, 0.f, 0.f, 0.f, 0.f, 0.f};
;     bf16x8 kf0, kf1, kf2, kf3, kf4, kf5, kf6, kf7;
;     ...
;     ATT_LOAD(a, 0); ATT_STORE(a, 0, 0); ATT_LOAD(a, 1); __syncthreads();
;     {
;         ATT_KRD(0);
;         pA0 = ATT_MFMA(kf0, qr[0], zero16); pA1 = ATT_MFMA(kf1, qr[0], zero16);
;         pA0 = ATT_MFMA(kf2, qr[1], pA0); pA1 = ATT_MFMA(kf3, qr[1], pA1);
;         pA0 = ATT_MFMA(kf4, qr[2], pA0); pA1 = ATT_MFMA(kf5, qr[2], pA1);
;         pA0 = ATT_MFMA(kf6, qr[3], pA0); pA1 = ATT_MFMA(kf7, qr[3], pA1);
.LBB0_456:
	v_mov_b32_e32 v239, v234
	s_ashr_i32 s4, s65, 7
	s_and_b32 s18, s65, 15
	v_readfirstlane_b32 s19, v239
	s_ashr_i32 s5, s4, 31
	s_lshr_b32 s16, s19, 1
	v_and_b32_e32 v30, 31, v239
	s_lshl_b64 s[4:5], s[4:5], 11
	s_lshl_b32 s37, s18, 7
	s_and_b32 s16, s16, 0x60
	s_or_b32 s82, s4, s37
	v_or_b32_e32 v240, s16, v30
	v_or_b32_e32 v2, s82, v240
	v_mov_b64_e32 v[0:1], s[6:7]
	v_mad_u64_u32 v[2:3], s[16:17], v2, s52, v[0:1]
	s_lshl_b32 s16, s65, 3
	v_mov_b32_e32 v4, 0x2800
	s_and_b32 s69, s16, 0x380
	v_ashrrev_i32_e32 v18, 3, v239
	v_mad_i32_i24 v3, s5, v4, v3
	s_lshl_b32 s70, s69, 1
	v_ashrrev_i32_e32 v19, 31, v18
	v_lshl_add_u64 v[16:17], v[2:3], 0, s[70:71]
	v_ashrrev_i32_e32 v20, 4, v239
	v_lshl_add_u64 v[2:3], s[4:5], 0, v[18:19]
	v_mad_u64_u32 v[4:5], s[16:17], v2, s52, v[0:1]
	v_ashrrev_i32_e32 v21, 31, v20
	v_mad_i32_i24 v5, v3, s52, v5
	v_lshl_add_u64 v[2:3], s[4:5], 0, v[20:21]
	v_mad_u64_u32 v[0:1], s[16:17], v2, s52, v[0:1]
	v_mad_i32_i24 v1, v3, s52, v1
	v_lshlrev_b32_e32 v2, 4, v239
	v_lshl_add_u64 v[0:1], v[0:1], 0, s[70:71]
	v_and_b32_e32 v22, 0xf0, v2
	v_mov_b32_e32 v23, v225
	v_lshl_add_u64 v[0:1], v[0:1], 0, v[22:23]
	s_mov_b64 s[16:17], 0x1000
	v_lshl_add_u64 v[226:227], v[0:1], 0, s[16:17]
	v_lshl_add_u64 v[0:1], v[4:5], 0, s[70:71]
	s_mul_i32 s70, s18, 0x140000
	v_and_b32_e32 v24, 0x70, v2
	v_mov_b32_e32 v25, v225
	v_lshl_add_u64 v[28:29], v[226:227], 0, s[70:71]
	v_lshl_add_u64 v[228:229], v[0:1], 0, v[24:25]
	v_add_co_u32_e32 v12, vcc, s59, v28
	v_lshl_add_u64 v[26:27], v[228:229], 0, s[70:71]
	s_nop 0
	v_addc_co_u32_e32 v13, vcc, 0, v29, vcc
	global_load_dwordx4 v[0:3], v[26:27], off offset:2048
	global_load_dwordx4 v[4:7], v[26:27], off offset:2176
	global_load_dwordx4 v[8:11], v[28:29], off
	s_nop 0
	global_load_dwordx4 v[12:15], v[12:13], off
	s_ashr_i32 s84, s19, 8
	s_lshl_b32 s16, s84, 6
	v_bfe_u32 v64, v239, 5, 1
	s_ashr_i32 s17, s16, 31
	v_lshl_add_u64 v[16:17], s[16:17], 1, v[16:17]
	v_lshlrev_b32_e32 v224, 4, v64
	v_lshl_add_u64 v[16:17], v[16:17], 0, v[224:225]
	global_load_dwordx4 v[156:159], v[16:17], off
	global_load_dwordx4 v[152:155], v[16:17], off offset:32
	global_load_dwordx4 v[148:151], v[16:17], off offset:64
	global_load_dwordx4 v[144:147], v[16:17], off offset:96
	s_movk_i32 s4, 0x140
	v_mul_lo_u32 v20, v20, s4
	s_movk_i32 s4, 0x90
	v_mul_u32_u24_e32 v21, 0x90, v30
	v_mad_u64_u32 v[18:19], s[16:17], v18, s4, v[24:25]
	s_mul_i32 s4, s84, 0x2400
	v_add3_u32 v242, v20, v22, 0
	v_add_co_u32_e32 v20, vcc, s60, v26
	v_add3_u32 v24, s4, v21, v224
	s_nop 0
	v_addc_co_u32_e32 v21, vcc, 0, v27, vcc
	v_add_co_u32_e32 v16, vcc, s60, v28
	v_add_u32_e32 v243, 0, v18
	s_mov_b64 s[16:17], 0xa0800
	v_addc_co_u32_e32 v17, vcc, 0, v29, vcc
	s_mov_b32 s4, 0xf0000
	v_lshl_add_u64 v[18:19], v[26:27], 0, s[16:17]
	v_add_co_u32_e32 v22, vcc, s4, v28
	global_load_dwordx4 v[48:51], v[20:21], off offset:2048
	global_load_dwordx4 v[52:55], v[18:19], off offset:128
	v_add_u32_e32 v244, 0, v24
	v_addc_co_u32_e32 v23, vcc, 0, v29, vcc
	v_lshlrev_b32_e32 v224, 2, v64
	s_addk_i32 s37, 0x80
	s_mov_b32 s83, s5
	s_and_b32 s5, s37, 0x780
	s_mul_i32 s70, s5, 0x2800
	s_mov_b32 s16, 0
	s_mov_b32 s17, s16
	s_mov_b32 s18, s16
	s_mov_b32 s19, s16
	s_mov_b32 s20, s16
	s_waitcnt vmcnt(9)
	ds_write_b128 v243, v[0:3]
	s_waitcnt vmcnt(8)
	ds_write_b128 v243, v[4:7] offset:9216
	s_waitcnt vmcnt(7)
	ds_write_b128 v242, v[8:11] offset:36864
	s_waitcnt vmcnt(6)
	ds_write_b128 v242, v[12:15] offset:47104
	global_load_dwordx4 v[56:59], v[16:17], off
	global_load_dwordx4 v[60:63], v[22:23], off
	s_waitcnt lgkmcnt(0)
	s_barrier
	ds_read_b128 v[0:3], v244
	ds_read_b128 v[4:7], v244 offset:32
	s_waitcnt vmcnt(7) lgkmcnt(1)
	v_mfma_f32_32x32x16_bf16 v[16:31], v[0:3], v[156:159], 0
	ds_read_b128 v[0:3], v244 offset:4608
	ds_read_b128 v[8:11], v244 offset:4640
	s_mov_b32 s21, s16
	s_mov_b32 s22, s16
	s_mov_b32 s23, s16
	s_mov_b32 s24, s16
	s_mov_b32 s25, s16
	s_mov_b32 s26, s16
	s_waitcnt lgkmcnt(1)
	v_mfma_f32_32x32x16_bf16 v[32:47], v[0:3], v[156:159], 0
	ds_read_b128 v[0:3], v244 offset:64
	s_mov_b32 s27, s16
	s_mov_b32 s28, s16
	s_mov_b32 s29, s16
	s_mov_b32 s30, s16
	s_mov_b32 s31, s16
	s_and_b32 s4, s64, 15
	s_waitcnt vmcnt(6)
	v_mfma_f32_32x32x16_bf16 v[16:31], v[4:7], v[152:155], v[16:31]
	v_lshrrev_b32_e32 v4, 2, v239
	v_and_or_b32 v4, v4, 3, v224
	v_mul_u32_u24_e32 v12, 0x140, v4
	v_lshlrev_b32_e32 v4, 1, v239
	v_and_b32_e32 v13, 32, v4
	s_lshl_b32 s4, s4, 7
	s_addk_i32 s4, 0x100
	s_waitcnt lgkmcnt(1)
	v_mfma_f32_32x32x16_bf16 v[32:47], v[8:11], v[152:155], v[32:47]
	ds_read_b128 v[4:7], v244 offset:4672
	ds_read_b128 v[8:11], v244 offset:96
	ds_read_b128 v[64:67], v244 offset:4704
	v_mov_b32_e32 v247, 0
	s_mov_b32 s5, -1
	s_waitcnt vmcnt(5) lgkmcnt(3)
	v_mfma_f32_32x32x16_bf16 v[16:31], v[0:3], v[148:151], v[16:31]
	v_lshlrev_b32_e32 v0, 3, v239
	v_and_b32_e32 v0, 24, v0
	v_or3_b32 v245, v12, v13, v0
	v_add_u32_e32 v246, 0, v245
	s_waitcnt lgkmcnt(2)
	v_mfma_f32_32x32x16_bf16 v[32:47], v[4:7], v[148:151], v[32:47]
	s_waitcnt vmcnt(4) lgkmcnt(1)
	v_mfma_f32_32x32x16_bf16 v[16:31], v[8:11], v[144:147], v[16:31]
	v_mov_b64_e32 v[0:1], s[16:17]
	v_mov_b64_e32 v[14:15], s[30:31]
	v_mov_b64_e32 v[2:3], s[18:19]
	v_mov_b64_e32 v[4:5], s[20:21]
	v_mov_b64_e32 v[6:7], s[22:23]
	v_mov_b64_e32 v[8:9], s[24:25]
	v_mov_b64_e32 v[10:11], s[26:27]
	s_waitcnt lgkmcnt(0)
; __device__ __forceinline__ float half_max(float m) { auto rr = __builtin_amdgcn_permlane32_swap(__float_as_uint(m), __float_as_uint(m), false, false); return max2f(__uint_as_float(rr[0]), __uint_as_float(rr[1])); }
; #define ATT_LOAD(S, t) do { const size_t o_ = (size_t)(((t) + rot) & 31) * 64 * PP; g##S##0 = *(const u32x4*)(kg + o_); g##S##1 = *(const u32x4*)(kg + o_ + 64); g##S##2 = *(const u32x4*)(vg + o_); g##S##3 = *(const u32x4*)(vg + o_ + (size_t)32 * PP); } while (0)
; #define ATT_STORE(S, ks, vs) do { *(LAS u32x4*)(lds + (ks) + kst) = g##S##0; *(LAS u32x4*)(lds + (ks) + 9216 + kst) = g##S##1; *(LAS u32x4*)(lds + (vs) + vst) = g##S##2; *(LAS u32x4*)(lds + (vs) + vst + 32 * 320) = g##S##3; } while (0)
; __device__ __forceinline__ void attn_unit(LAS unsigned char* lds, const bf16_t* PROJ, bf16_t* OCAT, const float* subg, float lam, float oml, int b, int h, int qb) {
;     ...
;         float mx = fmaxf(pA0[0], pA1[0]);
; #pragma unroll
;         for (int r = 1; r < 16; ++r) mx = fmaxf(mx, fmaxf(pA0[r], pA1[r]));
;         mrun = half_max(mx);
; #pragma unroll
;         for (int r = 0; r < 16; ++r) { pA0[r] = __builtin_amdgcn_exp2f(pA0[r] - mrun); pA1[r] = __builtin_amdgcn_exp2f(pA1[r] - mrun); negm[r] = -mrun; }
;         asm volatile("" : "+v"(negm));
;     }
;     ATT_STORE(a, KSL, VSL); ATT_LOAD(a, 2); __syncthreads();
;     ATT_KRD(KSL);
;     int vs_prev = 0, vs_store = 2 * VSL;
	v_mfma_f32_32x32x16_bf16 v[32:47], v[64:67], v[144:147], v[32:47]
	s_nop 2
	v_max_f32_e32 v65, v17, v17
	v_max_f32_e32 v66, v18, v18
	v_max_f32_e32 v67, v19, v19
	v_mov_b64_e32 v[12:13], s[28:29]
	s_mov_b32 s17, 0xa000
	s_nop 3
	v_max_f32_e32 v64, v33, v33
	v_max_f32_e32 v64, v65, v64
	v_max_f32_e32 v65, v34, v34
	v_max_f32_e32 v65, v66, v65
	v_max_f32_e32 v66, v35, v35
	v_max3_f32 v64, v16, v32, v64
	v_max_f32_e32 v66, v67, v66
	v_max3_f32 v64, v64, v65, v66
	v_max_f32_e32 v65, v36, v36
	v_max_f32_e32 v66, v20, v20
	v_max_f32_e32 v65, v66, v65
	v_max_f32_e32 v66, v37, v37
	v_max_f32_e32 v67, v21, v21
	v_max_f32_e32 v66, v67, v66
	v_max3_f32 v64, v64, v65, v66
	v_max_f32_e32 v65, v38, v38
	v_max_f32_e32 v66, v22, v22
	v_max_f32_e32 v65, v66, v65
	v_max_f32_e32 v66, v39, v39
	v_max_f32_e32 v67, v23, v23
	v_max_f32_e32 v66, v67, v66
	v_max3_f32 v64, v64, v65, v66
	v_max_f32_e32 v65, v40, v40
	v_max_f32_e32 v66, v24, v24
	v_max_f32_e32 v65, v66, v65
	v_max_f32_e32 v66, v41, v41
	v_max_f32_e32 v67, v25, v25
	v_max_f32_e32 v66, v67, v66
	v_max3_f32 v64, v64, v65, v66
	v_max_f32_e32 v65, v42, v42
	v_max_f32_e32 v66, v26, v26
	v_max_f32_e32 v65, v66, v65
	v_max_f32_e32 v66, v43, v43
	v_max_f32_e32 v67, v27, v27
	v_max_f32_e32 v66, v67, v66
	v_max3_f32 v64, v64, v65, v66
	v_max_f32_e32 v65, v44, v44
	v_max_f32_e32 v66, v28, v28
	v_max_f32_e32 v65, v66, v65
	v_max_f32_e32 v66, v45, v45
	v_max_f32_e32 v67, v29, v29
	v_max_f32_e32 v66, v67, v66
	v_max3_f32 v64, v64, v65, v66
	v_max_f32_e32 v65, v46, v46
	v_max_f32_e32 v66, v30, v30
	v_max_f32_e32 v65, v66, v65
	v_max_f32_e32 v66, v47, v47
	v_max_f32_e32 v67, v31, v31
	v_max_f32_e32 v66, v67, v66
	v_max3_f32 v64, v64, v65, v66
	v_mov_b32_e32 v65, v64
	s_nop 1
	v_permlane32_swap_b32_e32 v64, v65
	v_max_f32_e32 v241, v64, v65
	s_nop 0
	v_sub_f32_e32 v16, v16, v241
	v_exp_f32_e32 v96, v16
	v_sub_f32_e32 v16, v32, v241
	v_exp_f32_e32 v80, v16
	v_sub_f32_e32 v16, v17, v241
	v_xor_b32_e32 v64, 0x80000000, v241
	v_exp_f32_e32 v97, v16
	v_sub_f32_e32 v16, v33, v241
	v_exp_f32_e32 v81, v16
	v_mov_b32_e32 v65, v64
	v_mov_b32_e32 v66, v64
	v_mov_b32_e32 v67, v64
	v_mov_b32_e32 v68, v64
	v_mov_b32_e32 v69, v64
	v_mov_b32_e32 v70, v64
	v_mov_b32_e32 v71, v64
	v_mov_b32_e32 v72, v64
	v_mov_b32_e32 v73, v64
	v_mov_b32_e32 v74, v64
	v_mov_b32_e32 v75, v64
	v_mov_b32_e32 v76, v64
	v_mov_b32_e32 v77, v64
	v_mov_b32_e32 v78, v64
	v_mov_b32_e32 v79, v64
	v_lshl_add_u64 v[16:17], v[228:229], 0, s[70:71]
	global_load_dwordx4 v[112:115], v[16:17], off offset:2048
	global_load_dwordx4 v[116:119], v[16:17], off offset:2176
	v_lshl_add_u64 v[16:17], v[226:227], 0, s[70:71]
	v_add_co_u32_e32 v32, vcc, s59, v16
	s_nop 1
	v_addc_co_u32_e32 v33, vcc, 0, v17, vcc
	global_load_dwordx4 v[120:123], v[16:17], off
	global_load_dwordx4 v[124:127], v[32:33], off
	v_sub_f32_e32 v16, v18, v241
	v_exp_f32_e32 v98, v16
	v_sub_f32_e32 v16, v34, v241
	v_exp_f32_e32 v82, v16
	v_sub_f32_e32 v16, v19, v241
	v_exp_f32_e32 v99, v16
	v_sub_f32_e32 v16, v35, v241
	v_exp_f32_e32 v83, v16
	v_sub_f32_e32 v16, v20, v241
	v_exp_f32_e32 v100, v16
	v_sub_f32_e32 v16, v36, v241
	v_exp_f32_e32 v84, v16
	v_sub_f32_e32 v16, v21, v241
	v_exp_f32_e32 v101, v16
	v_sub_f32_e32 v16, v37, v241
	v_exp_f32_e32 v85, v16
	v_sub_f32_e32 v16, v22, v241
	v_exp_f32_e32 v102, v16
	v_sub_f32_e32 v16, v38, v241
	v_exp_f32_e32 v86, v16
	v_sub_f32_e32 v16, v23, v241
	v_exp_f32_e32 v103, v16
	v_sub_f32_e32 v16, v39, v241
	v_exp_f32_e32 v87, v16
	v_sub_f32_e32 v16, v24, v241
	v_exp_f32_e32 v104, v16
	v_sub_f32_e32 v16, v40, v241
	v_exp_f32_e32 v88, v16
	v_sub_f32_e32 v16, v25, v241
	v_exp_f32_e32 v105, v16
	v_sub_f32_e32 v16, v41, v241
	v_exp_f32_e32 v89, v16
	v_sub_f32_e32 v16, v26, v241
	v_exp_f32_e32 v106, v16
	v_sub_f32_e32 v16, v42, v241
	v_exp_f32_e32 v90, v16
	v_sub_f32_e32 v16, v27, v241
	v_exp_f32_e32 v107, v16
	v_sub_f32_e32 v16, v43, v241
	v_exp_f32_e32 v91, v16
	v_sub_f32_e32 v16, v28, v241
	v_exp_f32_e32 v108, v16
	v_sub_f32_e32 v16, v44, v241
	v_exp_f32_e32 v92, v16
	v_sub_f32_e32 v16, v29, v241
	v_exp_f32_e32 v109, v16
	v_sub_f32_e32 v16, v45, v241
	v_exp_f32_e32 v93, v16
	v_sub_f32_e32 v16, v30, v241
	v_exp_f32_e32 v110, v16
	v_sub_f32_e32 v16, v46, v241
	v_exp_f32_e32 v94, v16
	v_sub_f32_e32 v16, v31, v241
	v_exp_f32_e32 v111, v16
	v_sub_f32_e32 v16, v47, v241
	v_exp_f32_e32 v95, v16
	s_waitcnt vmcnt(7)
	ds_write_b128 v243, v[48:51] offset:18432
	s_waitcnt vmcnt(6)
	ds_write_b128 v243, v[52:55] offset:27648
	v_add_u32_e32 v16, 0xe000, v242
	s_waitcnt vmcnt(5)
	ds_write_b128 v242, v[56:59] offset:57344
	s_waitcnt vmcnt(4)
	ds_write_b128 v16, v[60:63] offset:10240
	s_waitcnt lgkmcnt(0)
	s_barrier
	ds_read_b128 v[220:223], v244 offset:18432
	ds_read_b128 v[212:215], v244 offset:18464
	ds_read_b128 v[216:219], v244 offset:23040
	ds_read_b128 v[208:211], v244 offset:23072
	ds_read_b128 v[204:207], v244 offset:18496
	ds_read_b128 v[196:199], v244 offset:18528
	ds_read_b128 v[200:203], v244 offset:23104
	ds_read_b128 v[192:195], v244 offset:23136
	v_mov_b64_e32 v[62:63], v[14:15]
	v_mov_b64_e32 v[46:47], v[14:15]
	v_mov_b64_e32 v[30:31], v[14:15]
	v_mov_b64_e32 v[60:61], v[12:13]
	v_mov_b64_e32 v[58:59], v[10:11]
	v_mov_b64_e32 v[56:57], v[8:9]
	v_mov_b64_e32 v[54:55], v[6:7]
	v_mov_b64_e32 v[52:53], v[4:5]
	v_mov_b64_e32 v[50:51], v[2:3]
	v_mov_b64_e32 v[48:49], v[0:1]
	v_mov_b64_e32 v[44:45], v[12:13]
	v_mov_b64_e32 v[42:43], v[10:11]
	v_mov_b64_e32 v[40:41], v[8:9]
	v_mov_b64_e32 v[38:39], v[6:7]
	v_mov_b64_e32 v[36:37], v[4:5]
	v_mov_b64_e32 v[34:35], v[2:3]
	v_mov_b64_e32 v[32:33], v[0:1]
	v_mov_b64_e32 v[28:29], v[12:13]
	v_mov_b64_e32 v[26:27], v[10:11]
	v_mov_b64_e32 v[24:25], v[8:9]
	v_mov_b64_e32 v[22:23], v[6:7]
	v_mov_b64_e32 v[20:21], v[4:5]
	v_mov_b64_e32 v[18:19], v[2:3]
	v_mov_b64_e32 v[16:17], v[0:1]
	s_branch .LBB0_458
	.p2align 6

; template <bool SP2 = true, class Epi, class Sched>
; __device__ __forceinline__ void gemm_phase(LAS unsigned char* lds, const int K, const int lda, const int ldb, const Sched& S, const Epi& E) {
;     ...
;     f32x4 acc[2][2][4][2];
; #pragma unroll
;     for (int a = 0; a < 2; ++a)
; #pragma unroll
;         for (int b = 0; b < 2; ++b)
; #pragma unroll
;             for (int m = 0; m < 4; ++m)
; #pragma unroll
;                 for (int n = 0; n < 2; ++n) acc[a][b][m][n] = (f32x4){0.f, 0.f, 0.f, 0.f};
.LBB0_533:
	s_add_u32 s90, s24, 0x100
	v_mov_b32_e32 v0, 0
	s_addc_u32 s91, s25, 0
	s_mov_b32 s92, -2
	v_mov_b32_e32 v1, v0
	v_mov_b32_e32 v2, v0
	v_mov_b32_e32 v3, v0
	v_mov_b32_e32 v4, v0
	v_mov_b32_e32 v5, v0
	v_mov_b32_e32 v6, v0
	v_mov_b32_e32 v7, v0
	v_mov_b32_e32 v16, v0
	v_mov_b32_e32 v17, v0
	v_mov_b32_e32 v18, v0
	v_mov_b32_e32 v19, v0
	v_mov_b32_e32 v20, v0
	v_mov_b32_e32 v21, v0
	v_mov_b32_e32 v22, v0
	v_mov_b32_e32 v23, v0
	v_mov_b32_e32 v32, v0
	v_mov_b32_e32 v33, v0
	v_mov_b32_e32 v34, v0
	v_mov_b32_e32 v35, v0
	v_mov_b32_e32 v36, v0
	v_mov_b32_e32 v37, v0
	v_mov_b32_e32 v38, v0
	v_mov_b32_e32 v39, v0
	v_mov_b32_e32 v48, v0
	v_mov_b32_e32 v49, v0
	v_mov_b32_e32 v50, v0
	v_mov_b32_e32 v51, v0
	v_mov_b32_e32 v52, v0
	v_mov_b32_e32 v53, v0
	v_mov_b32_e32 v54, v0
	v_mov_b32_e32 v55, v0
	v_mov_b32_e32 v8, v0
	v_mov_b32_e32 v9, v0
	v_mov_b32_e32 v10, v0
	v_mov_b32_e32 v11, v0
	v_mov_b32_e32 v12, v0
	v_mov_b32_e32 v13, v0
	v_mov_b32_e32 v14, v0
	v_mov_b32_e32 v15, v0
	v_mov_b32_e32 v24, v0
	v_mov_b32_e32 v25, v0
	v_mov_b32_e32 v26, v0
	v_mov_b32_e32 v27, v0
	v_mov_b32_e32 v28, v0
	v_mov_b32_e32 v29, v0
	v_mov_b32_e32 v30, v0
	v_mov_b32_e32 v31, v0
	v_mov_b32_e32 v40, v0
	v_mov_b32_e32 v41, v0
	v_mov_b32_e32 v42, v0
	v_mov_b32_e32 v43, v0
	v_mov_b32_e32 v44, v0
	v_mov_b32_e32 v45, v0
	v_mov_b32_e32 v46, v0
	v_mov_b32_e32 v47, v0
	v_mov_b32_e32 v56, v0
	v_mov_b32_e32 v57, v0
	v_mov_b32_e32 v58, v0
	v_mov_b32_e32 v59, v0
	v_mov_b32_e32 v60, v0
	v_mov_b32_e32 v61, v0
	v_mov_b32_e32 v62, v0
	v_mov_b32_e32 v63, v0
	v_mov_b32_e32 v64, v0
	v_mov_b32_e32 v65, v0
	v_mov_b32_e32 v66, v0
	v_mov_b32_e32 v67, v0
	v_mov_b32_e32 v68, v0
	v_mov_b32_e32 v69, v0
	v_mov_b32_e32 v70, v0
	v_mov_b32_e32 v71, v0
	v_mov_b32_e32 v80, v0
	v_mov_b32_e32 v81, v0
	v_mov_b32_e32 v82, v0
	v_mov_b32_e32 v83, v0
	v_mov_b32_e32 v84, v0
	v_mov_b32_e32 v85, v0
	v_mov_b32_e32 v86, v0
	v_mov_b32_e32 v87, v0
	v_mov_b32_e32 v96, v0
	v_mov_b32_e32 v97, v0
	v_mov_b32_e32 v98, v0
	v_mov_b32_e32 v99, v0
	v_mov_b32_e32 v100, v0
	v_mov_b32_e32 v101, v0
	v_mov_b32_e32 v102, v0
	v_mov_b32_e32 v103, v0
	v_mov_b32_e32 v112, v0
	v_mov_b32_e32 v113, v0
	v_mov_b32_e32 v114, v0
	v_mov_b32_e32 v115, v0
	v_mov_b32_e32 v116, v0
	v_mov_b32_e32 v117, v0
	v_mov_b32_e32 v118, v0
	v_mov_b32_e32 v119, v0
	v_mov_b32_e32 v72, v0
	v_mov_b32_e32 v73, v0
	v_mov_b32_e32 v74, v0
	v_mov_b32_e32 v75, v0
	v_mov_b32_e32 v76, v0
	v_mov_b32_e32 v77, v0
	v_mov_b32_e32 v78, v0
	v_mov_b32_e32 v79, v0
	v_mov_b32_e32 v88, v0
	v_mov_b32_e32 v89, v0
	v_mov_b32_e32 v90, v0
	v_mov_b32_e32 v91, v0
	v_mov_b32_e32 v92, v0
	v_mov_b32_e32 v93, v0
	v_mov_b32_e32 v94, v0
	v_mov_b32_e32 v95, v0
	v_mov_b32_e32 v104, v0
	v_mov_b32_e32 v105, v0
	v_mov_b32_e32 v106, v0
	v_mov_b32_e32 v107, v0
	v_mov_b32_e32 v108, v0
	v_mov_b32_e32 v109, v0
	v_mov_b32_e32 v110, v0
	v_mov_b32_e32 v111, v0
	v_mov_b32_e32 v120, v0
	v_mov_b32_e32 v121, v0
	v_mov_b32_e32 v122, v0
	v_mov_b32_e32 v123, v0
	v_mov_b32_e32 v124, v0
	v_mov_b32_e32 v125, v0
	v_mov_b32_e32 v126, v0
	v_mov_b32_e32 v127, v0
	.p2align 6

; #define PG8_BAR __builtin_amdgcn_s_barrier()
; template <bool SP2 = true, class Epi, class Sched>
; __device__ __forceinline__ void gemm_phase(LAS unsigned char* lds, const int K, const int lda, const int ldb, const Sched& S, const Epi& E) {
;     ...
; #pragma unroll
;         for (int a = 0; a < 2; ++a)
; #pragma unroll
;             for (int b = 0; b < 2; ++b)
; #pragma unroll
;                 for (int m = 0; m < 4; ++m)
; #pragma unroll
;                     for (int n = 0; n < 2; ++n) acc[a][b][m][n] = (f32x4){0.f, 0.f, 0.f, 0.f};
;         cur = nxt; cA = nA; cB = nB; ++ui;
;         if (wr == 1) PG8_BAR;
.LBB0_605:
	s_add_u32 s30, s30, 0x40080
	s_addc_u32 s31, s31, 0
	s_add_u32 s23, s82, 0x100
	v_mov_b32_e32 v0, 0
	s_addc_u32 s25, s83, 0
	s_mov_b32 s48, -2
	v_mov_b32_e32 v1, v0
	v_mov_b32_e32 v2, v0
	v_mov_b32_e32 v3, v0
	v_mov_b32_e32 v4, v0
	v_mov_b32_e32 v5, v0
	v_mov_b32_e32 v6, v0
	v_mov_b32_e32 v7, v0
	v_mov_b32_e32 v32, v0
	v_mov_b32_e32 v33, v0
	v_mov_b32_e32 v34, v0
	v_mov_b32_e32 v35, v0
	v_mov_b32_e32 v36, v0
	v_mov_b32_e32 v37, v0
	v_mov_b32_e32 v38, v0
	v_mov_b32_e32 v39, v0
	v_mov_b32_e32 v48, v0
	v_mov_b32_e32 v49, v0
	v_mov_b32_e32 v50, v0
	v_mov_b32_e32 v51, v0
	v_mov_b32_e32 v52, v0
	v_mov_b32_e32 v53, v0
	v_mov_b32_e32 v54, v0
	v_mov_b32_e32 v55, v0
	v_mov_b32_e32 v64, v0
	v_mov_b32_e32 v65, v0
	v_mov_b32_e32 v66, v0
	v_mov_b32_e32 v67, v0
	v_mov_b32_e32 v68, v0
	v_mov_b32_e32 v69, v0
	v_mov_b32_e32 v70, v0
	v_mov_b32_e32 v71, v0
	v_mov_b32_e32 v8, v0
	v_mov_b32_e32 v9, v0
	v_mov_b32_e32 v10, v0
	v_mov_b32_e32 v11, v0
	v_mov_b32_e32 v12, v0
	v_mov_b32_e32 v13, v0
	v_mov_b32_e32 v14, v0
	v_mov_b32_e32 v15, v0
	v_mov_b32_e32 v40, v0
	v_mov_b32_e32 v41, v0
	v_mov_b32_e32 v42, v0
	v_mov_b32_e32 v43, v0
	v_mov_b32_e32 v44, v0
	v_mov_b32_e32 v45, v0
	v_mov_b32_e32 v46, v0
	v_mov_b32_e32 v47, v0
	v_mov_b32_e32 v56, v0
	v_mov_b32_e32 v57, v0
	v_mov_b32_e32 v58, v0
	v_mov_b32_e32 v59, v0
	v_mov_b32_e32 v60, v0
	v_mov_b32_e32 v61, v0
	v_mov_b32_e32 v62, v0
	v_mov_b32_e32 v63, v0
	v_mov_b32_e32 v72, v0
	v_mov_b32_e32 v73, v0
	v_mov_b32_e32 v74, v0
	v_mov_b32_e32 v75, v0
	v_mov_b32_e32 v76, v0
	v_mov_b32_e32 v77, v0
	v_mov_b32_e32 v78, v0
	v_mov_b32_e32 v79, v0
	v_mov_b32_e32 v80, v0
	v_mov_b32_e32 v81, v0
	v_mov_b32_e32 v82, v0
	v_mov_b32_e32 v83, v0
	v_mov_b32_e32 v84, v0
	v_mov_b32_e32 v85, v0
	v_mov_b32_e32 v86, v0
	v_mov_b32_e32 v87, v0
	v_mov_b32_e32 v96, v0
	v_mov_b32_e32 v97, v0
	v_mov_b32_e32 v98, v0
	v_mov_b32_e32 v99, v0
	v_mov_b32_e32 v100, v0
	v_mov_b32_e32 v101, v0
	v_mov_b32_e32 v102, v0
	v_mov_b32_e32 v103, v0
	v_mov_b32_e32 v112, v0
	v_mov_b32_e32 v113, v0
	v_mov_b32_e32 v114, v0
	v_mov_b32_e32 v115, v0
	v_mov_b32_e32 v116, v0
	v_mov_b32_e32 v117, v0
	v_mov_b32_e32 v118, v0
	v_mov_b32_e32 v119, v0
	v_mov_b32_e32 v132, v0
	v_mov_b32_e32 v133, v0
	v_mov_b32_e32 v134, v0
	v_mov_b32_e32 v135, v0
	v_mov_b32_e32 v136, v0
	v_mov_b32_e32 v137, v0
	v_mov_b32_e32 v138, v0
	v_mov_b32_e32 v139, v0
	v_mov_b32_e32 v88, v0
	v_mov_b32_e32 v89, v0
	v_mov_b32_e32 v90, v0
	v_mov_b32_e32 v91, v0
	v_mov_b32_e32 v92, v0
	v_mov_b32_e32 v93, v0
	v_mov_b32_e32 v94, v0
	v_mov_b32_e32 v95, v0
	v_mov_b32_e32 v104, v0
	v_mov_b32_e32 v105, v0
	v_mov_b32_e32 v106, v0
	v_mov_b32_e32 v107, v0
	v_mov_b32_e32 v108, v0
	v_mov_b32_e32 v109, v0
	v_mov_b32_e32 v110, v0
	v_mov_b32_e32 v111, v0
	v_mov_b32_e32 v120, v0
	v_mov_b32_e32 v121, v0
	v_mov_b32_e32 v122, v0
	v_mov_b32_e32 v123, v0
	v_mov_b32_e32 v124, v0
	v_mov_b32_e32 v125, v0
	v_mov_b32_e32 v126, v0
	v_mov_b32_e32 v127, v0
	v_mov_b32_e32 v140, v0
	v_mov_b32_e32 v141, v0
	v_mov_b32_e32 v142, v0
	v_mov_b32_e32 v143, v0
	v_mov_b32_e32 v144, v0
	v_mov_b32_e32 v145, v0
	v_mov_b32_e32 v146, v0
	v_mov_b32_e32 v147, v0
	.p2align 6

; template <bool SP2 = true, class Epi, class Sched>
; __device__ __forceinline__ void gemm_phase(LAS unsigned char* lds, const int K, const int lda, const int ldb, const Sched& S, const Epi& E) {
;     ...
;         const bool has_next = S.next(ui + 1, nxt);
;         const char* nA = has_next ? nxt.A : cA; const char* nB = has_next ? nxt.B : cB;
;         for (int t = 0; t < nt; t += 2) {
;             const bool last = (t == nt - 2);
;             const char* a1 = cA + (unsigned)(t + 1) * kstep;
;             const char* a2 = last ? nA : cA + (unsigned)(t + 2) * kstep; const char* b2 = last ? nB : cB + (unsigned)(t + 2) * kstep;
;     ...
; #pragma unroll
;         for (int a = 0; a < 2; ++a)
; #pragma unroll
;             for (int b = 0; b < 2; ++b)
; #pragma unroll
;                 for (int m = 0; m < 4; ++m)
; #pragma unroll
;                     for (int n = 0; n < 2; ++n) acc[a][b][m][n] = (f32x4){0.f, 0.f, 0.f, 0.f};
.LBB0_675:
	s_and_b64 s[6:7], s[80:81], exec
	s_cselect_b32 s38, s29, s83
	s_cselect_b32 s49, s28, s82
	s_add_u32 s6, s82, 0x80080
	v_mov_b32_e32 v0, 0
	s_addc_u32 s7, s83, 0
	s_mov_b32 s64, -2
	s_mov_b64 s[8:9], s[30:31]
	v_mov_b32_e32 v1, v0
	v_mov_b32_e32 v2, v0
	v_mov_b32_e32 v3, v0
	v_mov_b32_e32 v4, v0
	v_mov_b32_e32 v5, v0
	v_mov_b32_e32 v6, v0
	v_mov_b32_e32 v7, v0
	v_mov_b32_e32 v16, v0
	v_mov_b32_e32 v17, v0
	v_mov_b32_e32 v18, v0
	v_mov_b32_e32 v19, v0
	v_mov_b32_e32 v20, v0
	v_mov_b32_e32 v21, v0
	v_mov_b32_e32 v22, v0
	v_mov_b32_e32 v23, v0
	v_mov_b32_e32 v32, v0
	v_mov_b32_e32 v33, v0
	v_mov_b32_e32 v34, v0
	v_mov_b32_e32 v35, v0
	v_mov_b32_e32 v36, v0
	v_mov_b32_e32 v37, v0
	v_mov_b32_e32 v38, v0
	v_mov_b32_e32 v39, v0
	v_mov_b32_e32 v48, v0
	v_mov_b32_e32 v49, v0
	v_mov_b32_e32 v50, v0
	v_mov_b32_e32 v51, v0
	v_mov_b32_e32 v52, v0
	v_mov_b32_e32 v53, v0
	v_mov_b32_e32 v54, v0
	v_mov_b32_e32 v55, v0
	v_mov_b32_e32 v8, v0
	v_mov_b32_e32 v9, v0
	v_mov_b32_e32 v10, v0
	v_mov_b32_e32 v11, v0
	v_mov_b32_e32 v12, v0
	v_mov_b32_e32 v13, v0
	v_mov_b32_e32 v14, v0
	v_mov_b32_e32 v15, v0
	v_mov_b32_e32 v24, v0
	v_mov_b32_e32 v25, v0
	v_mov_b32_e32 v26, v0
	v_mov_b32_e32 v27, v0
	v_mov_b32_e32 v28, v0
	v_mov_b32_e32 v29, v0
	v_mov_b32_e32 v30, v0
	v_mov_b32_e32 v31, v0
	v_mov_b32_e32 v40, v0
	v_mov_b32_e32 v41, v0
	v_mov_b32_e32 v42, v0
	v_mov_b32_e32 v43, v0
	v_mov_b32_e32 v44, v0
	v_mov_b32_e32 v45, v0
	v_mov_b32_e32 v46, v0
	v_mov_b32_e32 v47, v0
	v_mov_b32_e32 v56, v0
	v_mov_b32_e32 v57, v0
	v_mov_b32_e32 v58, v0
	v_mov_b32_e32 v59, v0
	v_mov_b32_e32 v60, v0
	v_mov_b32_e32 v61, v0
	v_mov_b32_e32 v62, v0
	v_mov_b32_e32 v63, v0
	v_mov_b32_e32 v64, v0
	v_mov_b32_e32 v65, v0
	v_mov_b32_e32 v66, v0
	v_mov_b32_e32 v67, v0
	v_mov_b32_e32 v68, v0
	v_mov_b32_e32 v69, v0
	v_mov_b32_e32 v70, v0
	v_mov_b32_e32 v71, v0
	v_mov_b32_e32 v80, v0
	v_mov_b32_e32 v81, v0
	v_mov_b32_e32 v82, v0
	v_mov_b32_e32 v83, v0
	v_mov_b32_e32 v84, v0
	v_mov_b32_e32 v85, v0
	v_mov_b32_e32 v86, v0
	v_mov_b32_e32 v87, v0
	v_mov_b32_e32 v96, v0
	v_mov_b32_e32 v97, v0
	v_mov_b32_e32 v98, v0
	v_mov_b32_e32 v99, v0
	v_mov_b32_e32 v100, v0
	v_mov_b32_e32 v101, v0
	v_mov_b32_e32 v102, v0
	v_mov_b32_e32 v103, v0
	v_mov_b32_e32 v132, v0
	v_mov_b32_e32 v133, v0
	v_mov_b32_e32 v134, v0
	v_mov_b32_e32 v135, v0
	v_mov_b32_e32 v136, v0
	v_mov_b32_e32 v137, v0
	v_mov_b32_e32 v138, v0
	v_mov_b32_e32 v139, v0
	v_mov_b32_e32 v72, v0
	v_mov_b32_e32 v73, v0
	v_mov_b32_e32 v74, v0
	v_mov_b32_e32 v75, v0
	v_mov_b32_e32 v76, v0
	v_mov_b32_e32 v77, v0
	v_mov_b32_e32 v78, v0
	v_mov_b32_e32 v79, v0
	v_mov_b32_e32 v88, v0
	v_mov_b32_e32 v89, v0
	v_mov_b32_e32 v90, v0
	v_mov_b32_e32 v91, v0
	v_mov_b32_e32 v92, v0
	v_mov_b32_e32 v93, v0
	v_mov_b32_e32 v94, v0
	v_mov_b32_e32 v95, v0
	v_mov_b32_e32 v104, v0
	v_mov_b32_e32 v105, v0
	v_mov_b32_e32 v106, v0
	v_mov_b32_e32 v107, v0
	v_mov_b32_e32 v108, v0
	v_mov_b32_e32 v109, v0
	v_mov_b32_e32 v110, v0
	v_mov_b32_e32 v111, v0
	v_mov_b32_e32 v120, v0
	v_mov_b32_e32 v121, v0
	v_mov_b32_e32 v122, v0
	v_mov_b32_e32 v123, v0
	v_mov_b32_e32 v124, v0
	v_mov_b32_e32 v125, v0
	v_mov_b32_e32 v126, v0
	v_mov_b32_e32 v127, v0
	.p2align 6
